# same setprio de-toggle in the GLU, out_proj and S3 K loops as well
# baseline (speedup 1.0000x reference)
; #define PG8_STAGE(bufoff, gbase, voff) do { _Pragma("unroll") for (int _i = 0; _i < 2; ++_i) \
;         __builtin_amdgcn_global_load_lds((const unsigned*)((const char*)(gbase) + (voff)[_i]), (LAS unsigned*)(lds + (bufoff) + ldsw + _i * 8192), 16, 0, 0); } while (0)
; #define PG8_LDA(dst, b, h) do { _Pragma("unroll") for (int m = 0; m < 4; ++m) _Pragma("unroll") for (int k = 0; k < 2; ++k) dst[m][k] = *(const LAS bf16x8*)(lds + PG8_SA(b, h) + aoff + m * 2048 + k * 1024); } while (0)
; #define PG8_LDB(dst, b, h) do { _Pragma("unroll") for (int n = 0; n < 2; ++n) _Pragma("unroll") for (int k = 0; k < 2; ++k) dst[n][k] = *(const LAS bf16x8*)(lds + PG8_SB(b, h) + boff + n * 2048 + k * 1024); } while (0)
; #define PG8_MMA(ai, bj, At, Bt) do { __builtin_amdgcn_s_setprio(1); _Pragma("unroll") for (int m = 0; m < 4; ++m) _Pragma("unroll") for (int n = 0; n < 2; ++n) _Pragma("unroll") for (int k = 0; k < 2; ++k) \
;         acc[ai][bj][m][n] = __builtin_amdgcn_mfma_f32_16x16x32_bf16(Bt[n][k], At[m][k], acc[ai][bj][m][n], 0, 0, 0); __builtin_amdgcn_s_setprio(0); } while (0)
; #define PG8_WAIT_V(n) asm volatile("s_waitcnt vmcnt(" #n ")" ::: "memory")
; #define PG8_WAIT_L(n) asm volatile("s_waitcnt lgkmcnt(" #n ")" ::: "memory")
; #define PG8_BAR __builtin_amdgcn_s_barrier()
; #define PG8_SCHED __builtin_amdgcn_sched_barrier(0)
; template <bool SP2 = true, class Epi, class Sched>
; __device__ __forceinline__ void gemm_phase(LAS unsigned char* lds, const int K, const int lda, const int ldb, const Sched& S, const Epi& E) {
;     ...
;             PG8_LDB(B0, 0, 0); PG8_LDB(B1, 0, 1); PG8_SCHED; PG8_LDA(At, 0, 0); PG8_STAGE(PG8_SA(1, 1), a1 + hstepA, voffA);
;             PG8_WAIT_V(8); PG8_WAIT_L(0); PG8_BAR; PG8_MMA(0, 0, At, B0); PG8_MMA(0, 1, At, B1); PG8_BAR; PG8_SCHED;
;             PG8_LDA(At, 0, 1); PG8_STAGE(PG8_SB(0, 0), b2, voffB); PG8_STAGE(PG8_SB(0, 1), b2 + hstepB, voffB); PG8_STAGE(PG8_SA(0, 0), a2, voffA);
;             PG8_WAIT_V(8); PG8_WAIT_L(0); PG8_BAR; PG8_MMA(1, 0, At, B0); PG8_MMA(1, 1, At, B1); PG8_BAR; PG8_SCHED;
.LBB0_534:
	s_add_u32 s24, s22, 0x100
	s_addc_u32 s25, s23, 0
	s_add_i32 s93, 0, 0x10000
	s_cmp_eq_u32 s92, 8
	s_cselect_b32 s29, s19, s25
	s_cselect_b32 s28, s18, s24
	v_add_u32_e32 v155, s93, v145
	s_cselect_b32 s27, s21, s91
	s_cselect_b32 s26, s20, s90
	s_add_i32 s94, 0, 0x14000
	ds_read_b128 v[140:143], v155
	ds_read_b128 v[156:159], v155 offset:1024
	ds_read_b128 v[160:163], v155 offset:2048
	ds_read_b128 v[164:167], v155 offset:3072
	v_add_u32_e32 v155, s94, v145
	ds_read_b128 v[168:171], v155
	ds_read_b128 v[172:175], v155 offset:1024
	ds_read_b128 v[176:179], v155 offset:2048
	ds_read_b128 v[180:183], v155 offset:3072
	v_lshl_add_u64 v[216:217], s[22:23], 0, v[136:137]
	s_add_i32 m0, s65, 0xc000
	ds_read_b128 v[184:187], v154
	ds_read_b128 v[188:191], v154 offset:1024
	ds_read_b128 v[192:195], v154 offset:2048
	ds_read_b128 v[196:199], v154 offset:3072
	ds_read_b128 v[200:203], v154 offset:4096
	ds_read_b128 v[204:207], v154 offset:5120
	ds_read_b128 v[208:211], v154 offset:6144
	ds_read_b128 v[212:215], v154 offset:7168
	global_load_lds_dwordx4 v[216:217], off
	v_lshl_add_u64 v[216:217], s[22:23], 0, v[138:139]
	s_add_i32 m0, s65, 0xe000
	s_nop 0
	global_load_lds_dwordx4 v[216:217], off
	s_waitcnt vmcnt(8)
	s_waitcnt lgkmcnt(0)
	s_barrier
	s_setprio 1
	s_waitcnt lgkmcnt(0)
	v_mfma_f32_16x16x32_bf16 v[124:127], v[140:143], v[184:187], v[124:127]
	v_mfma_f32_16x16x32_bf16 v[120:123], v[160:163], v[184:187], v[120:123]
	v_mfma_f32_16x16x32_bf16 v[108:111], v[140:143], v[192:195], v[108:111]
	v_mfma_f32_16x16x32_bf16 v[104:107], v[160:163], v[192:195], v[104:107]
	v_mfma_f32_16x16x32_bf16 v[92:95], v[140:143], v[200:203], v[92:95]
	v_mfma_f32_16x16x32_bf16 v[88:91], v[160:163], v[200:203], v[88:91]
	v_mfma_f32_16x16x32_bf16 v[76:79], v[140:143], v[208:211], v[76:79]
	v_mfma_f32_16x16x32_bf16 v[72:75], v[160:163], v[208:211], v[72:75]
	v_mfma_f32_16x16x32_bf16 v[124:127], v[156:159], v[188:191], v[124:127]
	v_mfma_f32_16x16x32_bf16 v[120:123], v[164:167], v[188:191], v[120:123]
	v_mfma_f32_16x16x32_bf16 v[108:111], v[156:159], v[196:199], v[108:111]
	v_mfma_f32_16x16x32_bf16 v[104:107], v[164:167], v[196:199], v[104:107]
	v_mfma_f32_16x16x32_bf16 v[92:95], v[156:159], v[204:207], v[92:95]
	v_mfma_f32_16x16x32_bf16 v[88:91], v[164:167], v[204:207], v[88:91]
	v_mfma_f32_16x16x32_bf16 v[76:79], v[156:159], v[212:215], v[76:79]
	v_mfma_f32_16x16x32_bf16 v[72:75], v[164:167], v[212:215], v[72:75]
	v_mfma_f32_16x16x32_bf16 v[116:119], v[168:171], v[184:187], v[116:119]
	v_mfma_f32_16x16x32_bf16 v[112:115], v[176:179], v[184:187], v[112:115]
	v_mfma_f32_16x16x32_bf16 v[100:103], v[168:171], v[192:195], v[100:103]
	v_mfma_f32_16x16x32_bf16 v[96:99], v[176:179], v[192:195], v[96:99]
	v_mfma_f32_16x16x32_bf16 v[84:87], v[168:171], v[200:203], v[84:87]
	v_mfma_f32_16x16x32_bf16 v[80:83], v[176:179], v[200:203], v[80:83]
	v_mfma_f32_16x16x32_bf16 v[68:71], v[168:171], v[208:211], v[68:71]
	v_mfma_f32_16x16x32_bf16 v[64:67], v[176:179], v[208:211], v[64:67]
	v_mfma_f32_16x16x32_bf16 v[116:119], v[172:175], v[188:191], v[116:119]
	v_mfma_f32_16x16x32_bf16 v[112:115], v[180:183], v[188:191], v[112:115]
	v_mfma_f32_16x16x32_bf16 v[100:103], v[172:175], v[196:199], v[100:103]
	v_mfma_f32_16x16x32_bf16 v[96:99], v[180:183], v[196:199], v[96:99]
	v_mfma_f32_16x16x32_bf16 v[84:87], v[172:175], v[204:207], v[84:87]
	v_mfma_f32_16x16x32_bf16 v[80:83], v[180:183], v[204:207], v[80:83]
	v_mfma_f32_16x16x32_bf16 v[68:71], v[172:175], v[212:215], v[68:71]
	v_mfma_f32_16x16x32_bf16 v[64:67], v[180:183], v[212:215], v[64:67]
	s_setprio 0
	s_barrier
	s_add_i32 s22, s93, s64
	v_lshl_add_u64 v[216:217], s[26:27], 0, v[132:133]
	s_mov_b32 m0, s22
	ds_read_b128 v[184:187], v154 offset:16384
	ds_read_b128 v[188:191], v154 offset:17408
	ds_read_b128 v[192:195], v154 offset:18432
	ds_read_b128 v[196:199], v154 offset:19456
	ds_read_b128 v[200:203], v154 offset:20480
	ds_read_b128 v[204:207], v154 offset:21504
	ds_read_b128 v[208:211], v154 offset:22528
	ds_read_b128 v[212:215], v154 offset:23552
	global_load_lds_dwordx4 v[216:217], off
	s_add_i32 m0, s22, 0x2000
	s_add_u32 s22, s26, 0x30000
	v_lshl_add_u64 v[218:219], s[26:27], 0, v[128:129]
	s_addc_u32 s23, s27, 0
	s_add_i32 s93, s94, s64
	global_load_lds_dwordx4 v[218:219], off
	v_lshl_add_u64 v[220:221], s[22:23], 0, v[132:133]
	s_mov_b32 m0, s93
	v_lshl_add_u64 v[222:223], s[28:29], 0, v[130:131]
	global_load_lds_dwordx4 v[220:221], off
	v_lshl_add_u64 v[220:221], s[22:23], 0, v[128:129]
	s_add_i32 m0, s93, 0x2000
	s_nop 0
	global_load_lds_dwordx4 v[220:221], off
	v_lshl_add_u64 v[220:221], s[28:29], 0, v[134:135]
	s_mov_b32 m0, s65
	s_nop 0
	global_load_lds_dwordx4 v[220:221], off
	s_mov_b32 m0, s69
	s_nop 0
	global_load_lds_dwordx4 v[222:223], off
	s_waitcnt vmcnt(8)
	s_waitcnt lgkmcnt(0)
	s_barrier
; #define PG8_STAGE(bufoff, gbase, voff) do { _Pragma("unroll") for (int _i = 0; _i < 2; ++_i) \
;         __builtin_amdgcn_global_load_lds((const unsigned*)((const char*)(gbase) + (voff)[_i]), (LAS unsigned*)(lds + (bufoff) + ldsw + _i * 8192), 16, 0, 0); } while (0)
; #define PG8_LDA(dst, b, h) do { _Pragma("unroll") for (int m = 0; m < 4; ++m) _Pragma("unroll") for (int k = 0; k < 2; ++k) dst[m][k] = *(const LAS bf16x8*)(lds + PG8_SA(b, h) + aoff + m * 2048 + k * 1024); } while (0)
; #define PG8_LDB(dst, b, h) do { _Pragma("unroll") for (int n = 0; n < 2; ++n) _Pragma("unroll") for (int k = 0; k < 2; ++k) dst[n][k] = *(const LAS bf16x8*)(lds + PG8_SB(b, h) + boff + n * 2048 + k * 1024); } while (0)
; #define PG8_MMA(ai, bj, At, Bt) do { __builtin_amdgcn_s_setprio(1); _Pragma("unroll") for (int m = 0; m < 4; ++m) _Pragma("unroll") for (int n = 0; n < 2; ++n) _Pragma("unroll") for (int k = 0; k < 2; ++k) \
;         acc[ai][bj][m][n] = __builtin_amdgcn_mfma_f32_16x16x32_bf16(Bt[n][k], At[m][k], acc[ai][bj][m][n], 0, 0, 0); __builtin_amdgcn_s_setprio(0); } while (0)
; #define PG8_WAIT_V(n) asm volatile("s_waitcnt vmcnt(" #n ")" ::: "memory")
; #define PG8_WAIT_L(n) asm volatile("s_waitcnt lgkmcnt(" #n ")" ::: "memory")
; #define PG8_BAR __builtin_amdgcn_s_barrier()
; #define PG8_SCHED __builtin_amdgcn_sched_barrier(0)
; template <bool SP2 = true, class Epi, class Sched>
; __device__ __forceinline__ void gemm_phase(LAS unsigned char* lds, const int K, const int lda, const int ldb, const Sched& S, const Epi& E) {
;     ...
;             PG8_WAIT_V(8); PG8_WAIT_L(0); PG8_BAR; PG8_MMA(1, 0, At, B0); PG8_MMA(1, 1, At, B1); PG8_BAR; PG8_SCHED;
;             PG8_LDB(B0, 1, 0); PG8_LDB(B1, 1, 1); PG8_SCHED; PG8_LDA(At, 1, 0); PG8_STAGE(PG8_SA(0, 1), a2 + hstepA, voffA);
;             PG8_WAIT_V(8); PG8_WAIT_L(0); PG8_BAR; PG8_MMA(0, 0, At, B0); PG8_MMA(0, 1, At, B1); PG8_BAR; PG8_SCHED;
	s_setprio 1
	s_waitcnt lgkmcnt(0)
	v_mfma_f32_16x16x32_bf16 v[60:63], v[140:143], v[184:187], v[60:63]
	v_mfma_f32_16x16x32_bf16 v[56:59], v[160:163], v[184:187], v[56:59]
	v_mfma_f32_16x16x32_bf16 v[44:47], v[140:143], v[192:195], v[44:47]
	v_mfma_f32_16x16x32_bf16 v[40:43], v[160:163], v[192:195], v[40:43]
	v_mfma_f32_16x16x32_bf16 v[28:31], v[140:143], v[200:203], v[28:31]
	v_mfma_f32_16x16x32_bf16 v[24:27], v[160:163], v[200:203], v[24:27]
	v_mfma_f32_16x16x32_bf16 v[12:15], v[140:143], v[208:211], v[12:15]
	v_mfma_f32_16x16x32_bf16 v[8:11], v[160:163], v[208:211], v[8:11]
	v_mfma_f32_16x16x32_bf16 v[60:63], v[156:159], v[188:191], v[60:63]
	v_mfma_f32_16x16x32_bf16 v[56:59], v[164:167], v[188:191], v[56:59]
	v_mfma_f32_16x16x32_bf16 v[44:47], v[156:159], v[196:199], v[44:47]
	v_mfma_f32_16x16x32_bf16 v[40:43], v[164:167], v[196:199], v[40:43]
	v_mfma_f32_16x16x32_bf16 v[28:31], v[156:159], v[204:207], v[28:31]
	v_mfma_f32_16x16x32_bf16 v[24:27], v[164:167], v[204:207], v[24:27]
	v_mfma_f32_16x16x32_bf16 v[12:15], v[156:159], v[212:215], v[12:15]
	v_mfma_f32_16x16x32_bf16 v[8:11], v[164:167], v[212:215], v[8:11]
	v_mfma_f32_16x16x32_bf16 v[52:55], v[168:171], v[184:187], v[52:55]
	v_mfma_f32_16x16x32_bf16 v[48:51], v[176:179], v[184:187], v[48:51]
	v_mfma_f32_16x16x32_bf16 v[36:39], v[168:171], v[192:195], v[36:39]
	v_mfma_f32_16x16x32_bf16 v[32:35], v[176:179], v[192:195], v[32:35]
	v_mfma_f32_16x16x32_bf16 v[20:23], v[168:171], v[200:203], v[20:23]
	v_mfma_f32_16x16x32_bf16 v[16:19], v[176:179], v[200:203], v[16:19]
	v_mfma_f32_16x16x32_bf16 v[4:7], v[168:171], v[208:211], v[4:7]
	v_mfma_f32_16x16x32_bf16 v[0:3], v[176:179], v[208:211], v[0:3]
	v_mfma_f32_16x16x32_bf16 v[52:55], v[172:175], v[188:191], v[52:55]
	v_mfma_f32_16x16x32_bf16 v[48:51], v[180:183], v[188:191], v[48:51]
	v_mfma_f32_16x16x32_bf16 v[36:39], v[172:175], v[196:199], v[36:39]
	v_mfma_f32_16x16x32_bf16 v[32:35], v[180:183], v[196:199], v[32:35]
	v_mfma_f32_16x16x32_bf16 v[20:23], v[172:175], v[204:207], v[20:23]
	v_mfma_f32_16x16x32_bf16 v[16:19], v[180:183], v[204:207], v[16:19]
	v_mfma_f32_16x16x32_bf16 v[4:7], v[172:175], v[212:215], v[4:7]
	v_mfma_f32_16x16x32_bf16 v[0:3], v[180:183], v[212:215], v[0:3]
	s_setprio 0
	s_barrier
	s_add_i32 s93, 0, 0x18000
	v_add_u32_e32 v155, s93, v145
	s_add_i32 s94, 0, 0x1c000
	ds_read_b128 v[140:143], v155
	ds_read_b128 v[156:159], v155 offset:1024
	ds_read_b128 v[160:163], v155 offset:2048
	ds_read_b128 v[164:167], v155 offset:3072
	v_add_u32_e32 v155, s94, v145
	ds_read_b128 v[168:171], v155
	ds_read_b128 v[172:175], v155 offset:1024
	ds_read_b128 v[176:179], v155 offset:2048
	ds_read_b128 v[180:183], v155 offset:3072
	s_add_u32 s22, s28, 0x30000
	s_addc_u32 s23, s29, 0
	s_mov_b32 m0, s70
	v_lshl_add_u64 v[226:227], s[22:23], 0, v[134:135]
	ds_read_b128 v[184:187], v154 offset:32768
	ds_read_b128 v[188:191], v154 offset:33792
	ds_read_b128 v[192:195], v154 offset:34816
	ds_read_b128 v[196:199], v154 offset:35840
	ds_read_b128 v[200:203], v154 offset:36864
	ds_read_b128 v[204:207], v154 offset:37888
	ds_read_b128 v[208:211], v154 offset:38912
	ds_read_b128 v[212:215], v154 offset:39936
	global_load_lds_dwordx4 v[226:227], off
	v_lshl_add_u64 v[226:227], s[22:23], 0, v[130:131]
	s_mov_b32 m0, s82
	s_nop 0
	global_load_lds_dwordx4 v[226:227], off
	s_waitcnt vmcnt(8)
	s_waitcnt lgkmcnt(0)
	s_barrier
	s_setprio 1
	s_waitcnt lgkmcnt(0)
	v_mfma_f32_16x16x32_bf16 v[124:127], v[140:143], v[184:187], v[124:127]
	v_mfma_f32_16x16x32_bf16 v[120:123], v[160:163], v[184:187], v[120:123]
	v_mfma_f32_16x16x32_bf16 v[108:111], v[140:143], v[192:195], v[108:111]
	v_mfma_f32_16x16x32_bf16 v[104:107], v[160:163], v[192:195], v[104:107]
	v_mfma_f32_16x16x32_bf16 v[92:95], v[140:143], v[200:203], v[92:95]
	v_mfma_f32_16x16x32_bf16 v[88:91], v[160:163], v[200:203], v[88:91]
	v_mfma_f32_16x16x32_bf16 v[76:79], v[140:143], v[208:211], v[76:79]
	v_mfma_f32_16x16x32_bf16 v[72:75], v[160:163], v[208:211], v[72:75]
	v_mfma_f32_16x16x32_bf16 v[124:127], v[156:159], v[188:191], v[124:127]
	v_mfma_f32_16x16x32_bf16 v[120:123], v[164:167], v[188:191], v[120:123]
	v_mfma_f32_16x16x32_bf16 v[108:111], v[156:159], v[196:199], v[108:111]
	v_mfma_f32_16x16x32_bf16 v[104:107], v[164:167], v[196:199], v[104:107]
	v_mfma_f32_16x16x32_bf16 v[92:95], v[156:159], v[204:207], v[92:95]
	v_mfma_f32_16x16x32_bf16 v[88:91], v[164:167], v[204:207], v[88:91]
	v_mfma_f32_16x16x32_bf16 v[76:79], v[156:159], v[212:215], v[76:79]
	v_mfma_f32_16x16x32_bf16 v[72:75], v[164:167], v[212:215], v[72:75]
	v_mfma_f32_16x16x32_bf16 v[116:119], v[168:171], v[184:187], v[116:119]
	v_mfma_f32_16x16x32_bf16 v[112:115], v[176:179], v[184:187], v[112:115]
	v_mfma_f32_16x16x32_bf16 v[100:103], v[168:171], v[192:195], v[100:103]
	v_mfma_f32_16x16x32_bf16 v[96:99], v[176:179], v[192:195], v[96:99]
	v_mfma_f32_16x16x32_bf16 v[84:87], v[168:171], v[200:203], v[84:87]
	v_mfma_f32_16x16x32_bf16 v[80:83], v[176:179], v[200:203], v[80:83]
	v_mfma_f32_16x16x32_bf16 v[68:71], v[168:171], v[208:211], v[68:71]
	v_mfma_f32_16x16x32_bf16 v[64:67], v[176:179], v[208:211], v[64:67]
	v_mfma_f32_16x16x32_bf16 v[116:119], v[172:175], v[188:191], v[116:119]
	v_mfma_f32_16x16x32_bf16 v[112:115], v[180:183], v[188:191], v[112:115]
	v_mfma_f32_16x16x32_bf16 v[100:103], v[172:175], v[196:199], v[100:103]
	v_mfma_f32_16x16x32_bf16 v[96:99], v[180:183], v[196:199], v[96:99]
	v_mfma_f32_16x16x32_bf16 v[84:87], v[172:175], v[204:207], v[84:87]
	v_mfma_f32_16x16x32_bf16 v[80:83], v[180:183], v[204:207], v[80:83]
	v_mfma_f32_16x16x32_bf16 v[68:71], v[172:175], v[212:215], v[68:71]
	v_mfma_f32_16x16x32_bf16 v[64:67], v[180:183], v[212:215], v[64:67]
	s_setprio 0
	s_barrier
; #define PG8_STAGE(bufoff, gbase, voff) do { _Pragma("unroll") for (int _i = 0; _i < 2; ++_i) \
;         __builtin_amdgcn_global_load_lds((const unsigned*)((const char*)(gbase) + (voff)[_i]), (LAS unsigned*)(lds + (bufoff) + ldsw + _i * 8192), 16, 0, 0); } while (0)
; #define PG8_LDA(dst, b, h) do { _Pragma("unroll") for (int m = 0; m < 4; ++m) _Pragma("unroll") for (int k = 0; k < 2; ++k) dst[m][k] = *(const LAS bf16x8*)(lds + PG8_SA(b, h) + aoff + m * 2048 + k * 1024); } while (0)
; #define PG8_MMA(ai, bj, At, Bt) do { __builtin_amdgcn_s_setprio(1); _Pragma("unroll") for (int m = 0; m < 4; ++m) _Pragma("unroll") for (int n = 0; n < 2; ++n) _Pragma("unroll") for (int k = 0; k < 2; ++k) \
;         acc[ai][bj][m][n] = __builtin_amdgcn_mfma_f32_16x16x32_bf16(Bt[n][k], At[m][k], acc[ai][bj][m][n], 0, 0, 0); __builtin_amdgcn_s_setprio(0); } while (0)
; #define PG8_WAIT_V(n) asm volatile("s_waitcnt vmcnt(" #n ")" ::: "memory")
; #define PG8_WAIT_L(n) asm volatile("s_waitcnt lgkmcnt(" #n ")" ::: "memory")
; #define PG8_BAR __builtin_amdgcn_s_barrier()
; #define PG8_SCHED __builtin_amdgcn_sched_barrier(0)
; template <bool SP2 = true, class Epi, class Sched>
; __device__ __forceinline__ void gemm_phase(LAS unsigned char* lds, const int K, const int lda, const int ldb, const Sched& S, const Epi& E) {
;     ...
;             PG8_LDA(At, 1, 1); PG8_STAGE(PG8_SB(1, 0), b3, voffB); PG8_STAGE(PG8_SB(1, 1), b3 + hstepB, voffB); PG8_STAGE(PG8_SA(1, 0), a3, voffA);
;             PG8_WAIT_V(8); PG8_WAIT_L(0); PG8_BAR; PG8_MMA(1, 0, At, B0); PG8_MMA(1, 1, At, B1); PG8_BAR; PG8_SCHED;
	s_add_i32 s22, s93, s64
	v_lshl_add_u64 v[216:217], v[216:217], 0, s[72:73]
	s_mov_b32 m0, s22
	ds_read_b128 v[184:187], v154 offset:49152
	ds_read_b128 v[188:191], v154 offset:50176
	ds_read_b128 v[192:195], v154 offset:51200
	ds_read_b128 v[196:199], v154 offset:52224
	ds_read_b128 v[200:203], v154 offset:53248
	ds_read_b128 v[204:207], v154 offset:54272
	ds_read_b128 v[208:211], v154 offset:55296
	ds_read_b128 v[212:215], v154 offset:56320
	global_load_lds_dwordx4 v[216:217], off
	s_add_i32 m0, s22, 0x2000
	s_add_u32 s22, s26, 0x30080
	v_lshl_add_u64 v[216:217], v[218:219], 0, s[72:73]
	s_addc_u32 s23, s27, 0
	s_add_i32 s26, s94, s64
	global_load_lds_dwordx4 v[216:217], off
	v_lshl_add_u64 v[216:217], s[22:23], 0, v[132:133]
	s_mov_b32 m0, s26
	s_nop 0
	global_load_lds_dwordx4 v[216:217], off
	v_lshl_add_u64 v[216:217], s[22:23], 0, v[128:129]
	s_add_i32 m0, s26, 0x2000
	s_nop 0
	global_load_lds_dwordx4 v[216:217], off
	v_lshl_add_u64 v[216:217], v[220:221], 0, s[72:73]
	s_mov_b32 m0, s83
	s_nop 0
	global_load_lds_dwordx4 v[216:217], off
	v_lshl_add_u64 v[216:217], v[222:223], 0, s[72:73]
	s_mov_b32 m0, s84
	s_nop 0
	global_load_lds_dwordx4 v[216:217], off
	s_waitcnt vmcnt(8)
	s_waitcnt lgkmcnt(0)
	s_barrier
	s_setprio 1
	s_waitcnt lgkmcnt(0)
	v_mfma_f32_16x16x32_bf16 v[60:63], v[140:143], v[184:187], v[60:63]
	v_mfma_f32_16x16x32_bf16 v[56:59], v[160:163], v[184:187], v[56:59]
	v_mfma_f32_16x16x32_bf16 v[44:47], v[140:143], v[192:195], v[44:47]
	v_mfma_f32_16x16x32_bf16 v[40:43], v[160:163], v[192:195], v[40:43]
	v_mfma_f32_16x16x32_bf16 v[28:31], v[140:143], v[200:203], v[28:31]
	v_mfma_f32_16x16x32_bf16 v[24:27], v[160:163], v[200:203], v[24:27]
	v_mfma_f32_16x16x32_bf16 v[12:15], v[140:143], v[208:211], v[12:15]
	v_mfma_f32_16x16x32_bf16 v[8:11], v[160:163], v[208:211], v[8:11]
	v_mfma_f32_16x16x32_bf16 v[60:63], v[156:159], v[188:191], v[60:63]
	v_mfma_f32_16x16x32_bf16 v[56:59], v[164:167], v[188:191], v[56:59]
	v_mfma_f32_16x16x32_bf16 v[44:47], v[156:159], v[196:199], v[44:47]
	v_mfma_f32_16x16x32_bf16 v[40:43], v[164:167], v[196:199], v[40:43]
	v_mfma_f32_16x16x32_bf16 v[28:31], v[156:159], v[204:207], v[28:31]
	v_mfma_f32_16x16x32_bf16 v[24:27], v[164:167], v[204:207], v[24:27]
	v_mfma_f32_16x16x32_bf16 v[12:15], v[156:159], v[212:215], v[12:15]
	v_mfma_f32_16x16x32_bf16 v[8:11], v[164:167], v[212:215], v[8:11]
	v_mfma_f32_16x16x32_bf16 v[52:55], v[168:171], v[184:187], v[52:55]
	v_mfma_f32_16x16x32_bf16 v[48:51], v[176:179], v[184:187], v[48:51]
	v_mfma_f32_16x16x32_bf16 v[36:39], v[168:171], v[192:195], v[36:39]
	v_mfma_f32_16x16x32_bf16 v[32:35], v[176:179], v[192:195], v[32:35]
	v_mfma_f32_16x16x32_bf16 v[20:23], v[168:171], v[200:203], v[20:23]
	v_mfma_f32_16x16x32_bf16 v[16:19], v[176:179], v[200:203], v[16:19]
	v_mfma_f32_16x16x32_bf16 v[4:7], v[168:171], v[208:211], v[4:7]
	v_mfma_f32_16x16x32_bf16 v[0:3], v[176:179], v[208:211], v[0:3]
	v_mfma_f32_16x16x32_bf16 v[52:55], v[172:175], v[188:191], v[52:55]
	v_mfma_f32_16x16x32_bf16 v[48:51], v[180:183], v[188:191], v[48:51]
	v_mfma_f32_16x16x32_bf16 v[36:39], v[172:175], v[196:199], v[36:39]
	v_mfma_f32_16x16x32_bf16 v[32:35], v[180:183], v[196:199], v[32:35]
	v_mfma_f32_16x16x32_bf16 v[20:23], v[172:175], v[204:207], v[20:23]
	v_mfma_f32_16x16x32_bf16 v[16:19], v[180:183], v[204:207], v[16:19]
	v_mfma_f32_16x16x32_bf16 v[4:7], v[172:175], v[212:215], v[4:7]
	v_mfma_f32_16x16x32_bf16 v[0:3], v[180:183], v[212:215], v[0:3]
	s_setprio 0
	s_barrier
	s_add_i32 s92, s92, 2
	s_add_u32 s90, s90, 0x100
	s_addc_u32 s91, s91, 0
	s_cmp_gt_u32 s92, 9
	s_mov_b64 s[22:23], s[24:25]
	s_cbranch_scc0 .LBB0_534
	s_and_b64 vcc, exec, s[16:17]
	s_cbranch_vccz .LBB0_537
	s_barrier

; #define PG8_STAGE(bufoff, gbase, voff) do { _Pragma("unroll") for (int _i = 0; _i < 2; ++_i) \
;         __builtin_amdgcn_global_load_lds((const unsigned*)((const char*)(gbase) + (voff)[_i]), (LAS unsigned*)(lds + (bufoff) + ldsw + _i * 8192), 16, 0, 0); } while (0)
; #define PG8_LDA(dst, b, h) do { _Pragma("unroll") for (int m = 0; m < 4; ++m) _Pragma("unroll") for (int k = 0; k < 2; ++k) dst[m][k] = *(const LAS bf16x8*)(lds + PG8_SA(b, h) + aoff + m * 2048 + k * 1024); } while (0)
; #define PG8_LDB(dst, b, h) do { _Pragma("unroll") for (int n = 0; n < 2; ++n) _Pragma("unroll") for (int k = 0; k < 2; ++k) dst[n][k] = *(const LAS bf16x8*)(lds + PG8_SB(b, h) + boff + n * 2048 + k * 1024); } while (0)
; #define PG8_MMA(ai, bj, At, Bt) do { __builtin_amdgcn_s_setprio(1); _Pragma("unroll") for (int m = 0; m < 4; ++m) _Pragma("unroll") for (int n = 0; n < 2; ++n) _Pragma("unroll") for (int k = 0; k < 2; ++k) \
;         acc[ai][bj][m][n] = __builtin_amdgcn_mfma_f32_16x16x32_bf16(Bt[n][k], At[m][k], acc[ai][bj][m][n], 0, 0, 0); __builtin_amdgcn_s_setprio(0); } while (0)
; #define PG8_WAIT_V(n) asm volatile("s_waitcnt vmcnt(" #n ")" ::: "memory")
; #define PG8_WAIT_L(n) asm volatile("s_waitcnt lgkmcnt(" #n ")" ::: "memory")
; #define PG8_BAR __builtin_amdgcn_s_barrier()
; #define PG8_SCHED __builtin_amdgcn_sched_barrier(0)
; template <bool SP2 = true, class Epi, class Sched>
; __device__ __forceinline__ void gemm_phase(LAS unsigned char* lds, const int K, const int lda, const int ldb, const Sched& S, const Epi& E) {
;     ...
;         for (int t = 0; t < nt; t += 2) {
;             const bool last = (t == nt - 2);
;             const char* a1 = cA + (unsigned)(t + 1) * kstep;
;             const char* a2 = last ? nA : cA + (unsigned)(t + 2) * kstep; const char* b2 = last ? nB : cB + (unsigned)(t + 2) * kstep;
;             const char* a3 = a2 + kstep; const char* b3 = b2 + kstep;
;             if constexpr (SP2) {
;             PG8_LDB(B0, 0, 0); PG8_LDB(B1, 0, 1); PG8_SCHED; PG8_LDA(At, 0, 0); PG8_STAGE(PG8_SA(1, 1), a1 + hstepA, voffA);
;             PG8_WAIT_V(8); PG8_WAIT_L(0); PG8_BAR; PG8_MMA(0, 0, At, B0); PG8_MMA(0, 1, At, B1); PG8_BAR; PG8_SCHED;
;             PG8_LDA(At, 0, 1); PG8_STAGE(PG8_SB(0, 0), b2, voffB); PG8_STAGE(PG8_SB(0, 1), b2 + hstepB, voffB); PG8_STAGE(PG8_SA(0, 0), a2, voffA);
.LBB0_606:
	s_add_u32 s49, s30, 0xfffc0080
	s_addc_u32 s82, s31, -1
	s_add_i32 s94, 0, 0x10000
	s_cmp_eq_u32 s48, 12
	s_cselect_b32 s85, s27, s82
	s_cselect_b32 s84, s26, s49
	s_cselect_b32 s83, s29, s25
	s_cselect_b32 s82, s28, s23
	s_add_i32 s49, 0, 0x14000
	v_add_u32_e32 v28, s94, v165
	v_add_u32_e32 v162, s49, v165
	ds_read_b128 v[16:19], v28
	ds_read_b128 v[20:23], v28 offset:1024
	ds_read_b128 v[24:27], v28 offset:2048
	ds_read_b128 v[28:31], v28 offset:3072
	ds_read_b128 v[128:131], v162
	ds_read_b128 v[158:161], v162 offset:1024
	ds_read_b128 v[168:171], v162 offset:2048
	ds_read_b128 v[172:175], v162 offset:3072
	v_lshl_add_u64 v[162:163], s[30:31], 0, v[154:155]
	s_add_i32 m0, s88, 0xc000
	ds_read_b128 v[176:179], v167
	ds_read_b128 v[180:183], v167 offset:1024
	ds_read_b128 v[184:187], v167 offset:2048
	ds_read_b128 v[188:191], v167 offset:3072
	ds_read_b128 v[192:195], v167 offset:4096
	ds_read_b128 v[196:199], v167 offset:5120
	ds_read_b128 v[200:203], v167 offset:6144
	ds_read_b128 v[204:207], v167 offset:7168
	global_load_lds_dwordx4 v[162:163], off
	v_lshl_add_u64 v[162:163], s[30:31], 0, v[156:157]
	s_add_i32 m0, s88, 0xe000
	s_nop 0
	global_load_lds_dwordx4 v[162:163], off
	s_waitcnt vmcnt(8)
	s_waitcnt lgkmcnt(0)
	s_barrier
	s_setprio 1
	s_waitcnt lgkmcnt(0)
	v_mfma_f32_16x16x32_bf16 v[144:147], v[16:19], v[176:179], v[144:147]
	v_mfma_f32_16x16x32_bf16 v[140:143], v[24:27], v[176:179], v[140:143]
	v_mfma_f32_16x16x32_bf16 v[124:127], v[16:19], v[184:187], v[124:127]
	v_mfma_f32_16x16x32_bf16 v[120:123], v[24:27], v[184:187], v[120:123]
	v_mfma_f32_16x16x32_bf16 v[108:111], v[16:19], v[192:195], v[108:111]
	v_mfma_f32_16x16x32_bf16 v[104:107], v[24:27], v[192:195], v[104:107]
	v_mfma_f32_16x16x32_bf16 v[92:95], v[16:19], v[200:203], v[92:95]
	v_mfma_f32_16x16x32_bf16 v[88:91], v[24:27], v[200:203], v[88:91]
	v_mfma_f32_16x16x32_bf16 v[144:147], v[20:23], v[180:183], v[144:147]
	v_mfma_f32_16x16x32_bf16 v[140:143], v[28:31], v[180:183], v[140:143]
	v_mfma_f32_16x16x32_bf16 v[124:127], v[20:23], v[188:191], v[124:127]
	v_mfma_f32_16x16x32_bf16 v[120:123], v[28:31], v[188:191], v[120:123]
	v_mfma_f32_16x16x32_bf16 v[108:111], v[20:23], v[196:199], v[108:111]
	v_mfma_f32_16x16x32_bf16 v[104:107], v[28:31], v[196:199], v[104:107]
	v_mfma_f32_16x16x32_bf16 v[92:95], v[20:23], v[204:207], v[92:95]
	v_mfma_f32_16x16x32_bf16 v[88:91], v[28:31], v[204:207], v[88:91]
	v_mfma_f32_16x16x32_bf16 v[136:139], v[128:131], v[176:179], v[136:139]
	v_mfma_f32_16x16x32_bf16 v[132:135], v[168:171], v[176:179], v[132:135]
	v_mfma_f32_16x16x32_bf16 v[116:119], v[128:131], v[184:187], v[116:119]
	v_mfma_f32_16x16x32_bf16 v[112:115], v[168:171], v[184:187], v[112:115]
	v_mfma_f32_16x16x32_bf16 v[100:103], v[128:131], v[192:195], v[100:103]
	v_mfma_f32_16x16x32_bf16 v[96:99], v[168:171], v[192:195], v[96:99]
	v_mfma_f32_16x16x32_bf16 v[84:87], v[128:131], v[200:203], v[84:87]
	v_mfma_f32_16x16x32_bf16 v[80:83], v[168:171], v[200:203], v[80:83]
	v_mfma_f32_16x16x32_bf16 v[136:139], v[158:161], v[180:183], v[136:139]
	v_mfma_f32_16x16x32_bf16 v[132:135], v[172:175], v[180:183], v[132:135]
	v_mfma_f32_16x16x32_bf16 v[116:119], v[158:161], v[188:191], v[116:119]
	v_mfma_f32_16x16x32_bf16 v[112:115], v[172:175], v[188:191], v[112:115]
	v_mfma_f32_16x16x32_bf16 v[100:103], v[158:161], v[196:199], v[100:103]
	v_mfma_f32_16x16x32_bf16 v[96:99], v[172:175], v[196:199], v[96:99]
	v_mfma_f32_16x16x32_bf16 v[84:87], v[158:161], v[204:207], v[84:87]
	v_mfma_f32_16x16x32_bf16 v[80:83], v[172:175], v[204:207], v[80:83]
	s_setprio 0
	s_barrier
	s_add_i32 s94, s94, s87
	v_lshl_add_u64 v[162:163], s[82:83], 0, v[224:225]
	s_mov_b32 m0, s94
	ds_read_b128 v[176:179], v167 offset:16384
	ds_read_b128 v[180:183], v167 offset:17408
	ds_read_b128 v[184:187], v167 offset:18432
	ds_read_b128 v[188:191], v167 offset:19456
	ds_read_b128 v[192:195], v167 offset:20480
	ds_read_b128 v[196:199], v167 offset:21504
	ds_read_b128 v[200:203], v167 offset:22528
	ds_read_b128 v[204:207], v167 offset:23552
	global_load_lds_dwordx4 v[162:163], off
	s_add_i32 m0, s94, 0x2000
	s_add_u32 s94, s82, 0x40000
	v_lshl_add_u64 v[208:209], s[82:83], 0, v[148:149]
	s_addc_u32 s95, s83, 0
	s_add_i32 s49, s49, s87
	global_load_lds_dwordx4 v[208:209], off
	v_lshl_add_u64 v[210:211], s[94:95], 0, v[224:225]
	s_mov_b32 m0, s49
	v_lshl_add_u64 v[212:213], s[84:85], 0, v[150:151]
	global_load_lds_dwordx4 v[210:211], off
	v_lshl_add_u64 v[210:211], s[94:95], 0, v[148:149]
	s_add_i32 m0, s49, 0x2000
	s_nop 0
	global_load_lds_dwordx4 v[210:211], off
	v_lshl_add_u64 v[210:211], s[84:85], 0, v[152:153]
	s_mov_b32 m0, s88
	s_nop 0
	global_load_lds_dwordx4 v[210:211], off
	s_mov_b32 m0, s89
	s_nop 0
	global_load_lds_dwordx4 v[212:213], off
	s_waitcnt vmcnt(8)
	s_waitcnt lgkmcnt(0)
	s_barrier
; #define PG8_STAGE(bufoff, gbase, voff) do { _Pragma("unroll") for (int _i = 0; _i < 2; ++_i) \
;         __builtin_amdgcn_global_load_lds((const unsigned*)((const char*)(gbase) + (voff)[_i]), (LAS unsigned*)(lds + (bufoff) + ldsw + _i * 8192), 16, 0, 0); } while (0)
; #define PG8_LDA(dst, b, h) do { _Pragma("unroll") for (int m = 0; m < 4; ++m) _Pragma("unroll") for (int k = 0; k < 2; ++k) dst[m][k] = *(const LAS bf16x8*)(lds + PG8_SA(b, h) + aoff + m * 2048 + k * 1024); } while (0)
; #define PG8_LDB(dst, b, h) do { _Pragma("unroll") for (int n = 0; n < 2; ++n) _Pragma("unroll") for (int k = 0; k < 2; ++k) dst[n][k] = *(const LAS bf16x8*)(lds + PG8_SB(b, h) + boff + n * 2048 + k * 1024); } while (0)
; #define PG8_MMA(ai, bj, At, Bt) do { __builtin_amdgcn_s_setprio(1); _Pragma("unroll") for (int m = 0; m < 4; ++m) _Pragma("unroll") for (int n = 0; n < 2; ++n) _Pragma("unroll") for (int k = 0; k < 2; ++k) \
;         acc[ai][bj][m][n] = __builtin_amdgcn_mfma_f32_16x16x32_bf16(Bt[n][k], At[m][k], acc[ai][bj][m][n], 0, 0, 0); __builtin_amdgcn_s_setprio(0); } while (0)
; #define PG8_WAIT_V(n) asm volatile("s_waitcnt vmcnt(" #n ")" ::: "memory")
; #define PG8_WAIT_L(n) asm volatile("s_waitcnt lgkmcnt(" #n ")" ::: "memory")
; #define PG8_BAR __builtin_amdgcn_s_barrier()
; #define PG8_SCHED __builtin_amdgcn_sched_barrier(0)
; template <bool SP2 = true, class Epi, class Sched>
; __device__ __forceinline__ void gemm_phase(LAS unsigned char* lds, const int K, const int lda, const int ldb, const Sched& S, const Epi& E) {
;     ...
;             PG8_WAIT_V(8); PG8_WAIT_L(0); PG8_BAR; PG8_MMA(0, 0, At, B0); PG8_MMA(0, 1, At, B1); PG8_BAR; PG8_SCHED;
;             PG8_LDA(At, 0, 1); PG8_STAGE(PG8_SB(0, 0), b2, voffB); PG8_STAGE(PG8_SB(0, 1), b2 + hstepB, voffB); PG8_STAGE(PG8_SA(0, 0), a2, voffA);
;             PG8_WAIT_V(8); PG8_WAIT_L(0); PG8_BAR; PG8_MMA(1, 0, At, B0); PG8_MMA(1, 1, At, B1); PG8_BAR; PG8_SCHED;
;             PG8_LDB(B0, 1, 0); PG8_LDB(B1, 1, 1); PG8_SCHED; PG8_LDA(At, 1, 0); PG8_STAGE(PG8_SA(0, 1), a2 + hstepA, voffA);
;             PG8_WAIT_V(8); PG8_WAIT_L(0); PG8_BAR; PG8_MMA(0, 0, At, B0); PG8_MMA(0, 1, At, B1); PG8_BAR; PG8_SCHED;
	s_setprio 1
	s_waitcnt lgkmcnt(0)
	v_mfma_f32_16x16x32_bf16 v[76:79], v[16:19], v[176:179], v[76:79]
	v_mfma_f32_16x16x32_bf16 v[72:75], v[24:27], v[176:179], v[72:75]
	v_mfma_f32_16x16x32_bf16 v[60:63], v[16:19], v[184:187], v[60:63]
	v_mfma_f32_16x16x32_bf16 v[56:59], v[24:27], v[184:187], v[56:59]
	v_mfma_f32_16x16x32_bf16 v[44:47], v[16:19], v[192:195], v[44:47]
	v_mfma_f32_16x16x32_bf16 v[40:43], v[24:27], v[192:195], v[40:43]
	v_mfma_f32_16x16x32_bf16 v[12:15], v[16:19], v[200:203], v[12:15]
	v_mfma_f32_16x16x32_bf16 v[8:11], v[24:27], v[200:203], v[8:11]
	v_mfma_f32_16x16x32_bf16 v[76:79], v[20:23], v[180:183], v[76:79]
	v_mfma_f32_16x16x32_bf16 v[72:75], v[28:31], v[180:183], v[72:75]
	v_mfma_f32_16x16x32_bf16 v[60:63], v[20:23], v[188:191], v[60:63]
	v_mfma_f32_16x16x32_bf16 v[56:59], v[28:31], v[188:191], v[56:59]
	v_mfma_f32_16x16x32_bf16 v[44:47], v[20:23], v[196:199], v[44:47]
	v_mfma_f32_16x16x32_bf16 v[40:43], v[28:31], v[196:199], v[40:43]
	v_mfma_f32_16x16x32_bf16 v[12:15], v[20:23], v[204:207], v[12:15]
	v_mfma_f32_16x16x32_bf16 v[8:11], v[28:31], v[204:207], v[8:11]
	v_mfma_f32_16x16x32_bf16 v[36:39], v[128:131], v[192:195], v[36:39]
	v_mfma_f32_16x16x32_bf16 v[32:35], v[168:171], v[192:195], v[32:35]
	v_mfma_f32_16x16x32_bf16 v[4:7], v[128:131], v[200:203], v[4:7]
	v_mfma_f32_16x16x32_bf16 v[0:3], v[168:171], v[200:203], v[0:3]
	v_mfma_f32_16x16x32_bf16 v[16:19], v[128:131], v[176:179], v[68:71]
	v_mfma_f32_16x16x32_bf16 v[20:23], v[168:171], v[176:179], v[64:67]
	v_mfma_f32_16x16x32_bf16 v[24:27], v[128:131], v[184:187], v[52:55]
	v_mfma_f32_16x16x32_bf16 v[28:31], v[168:171], v[184:187], v[48:51]
	v_mfma_f32_16x16x32_bf16 v[36:39], v[158:161], v[196:199], v[36:39]
	v_mfma_f32_16x16x32_bf16 v[32:35], v[172:175], v[196:199], v[32:35]
	v_mfma_f32_16x16x32_bf16 v[4:7], v[158:161], v[204:207], v[4:7]
	v_mfma_f32_16x16x32_bf16 v[0:3], v[172:175], v[204:207], v[0:3]
	v_mfma_f32_16x16x32_bf16 v[16:19], v[158:161], v[180:183], v[16:19]
	v_mfma_f32_16x16x32_bf16 v[20:23], v[172:175], v[180:183], v[20:23]
	v_mfma_f32_16x16x32_bf16 v[24:27], v[158:161], v[188:191], v[24:27]
	v_mfma_f32_16x16x32_bf16 v[28:31], v[172:175], v[188:191], v[28:31]
	s_setprio 0
	s_barrier
	s_add_i32 s49, 0, 0x18000
	s_add_i32 s94, 0, 0x1c000
	v_add_u32_e32 v68, s49, v165
	v_add_u32_e32 v172, s94, v165
	ds_read_b128 v[48:51], v68
	ds_read_b128 v[52:55], v68 offset:1024
	ds_read_b128 v[64:67], v68 offset:2048
	ds_read_b128 v[68:71], v68 offset:3072
	ds_read_b128 v[128:131], v172
	ds_read_b128 v[158:161], v172 offset:1024
	ds_read_b128 v[168:171], v172 offset:2048
	ds_read_b128 v[172:175], v172 offset:3072
	s_add_u32 s84, s84, 0x40000
	s_addc_u32 s85, s85, 0
	s_mov_b32 m0, s90
	v_lshl_add_u64 v[214:215], s[84:85], 0, v[152:153]
	ds_read_b128 v[176:179], v167 offset:32768
	ds_read_b128 v[180:183], v167 offset:33792
	ds_read_b128 v[184:187], v167 offset:34816
	ds_read_b128 v[188:191], v167 offset:35840
	ds_read_b128 v[192:195], v167 offset:36864
	ds_read_b128 v[196:199], v167 offset:37888
	ds_read_b128 v[200:203], v167 offset:38912
	ds_read_b128 v[204:207], v167 offset:39936
	global_load_lds_dwordx4 v[214:215], off
	v_lshl_add_u64 v[214:215], s[84:85], 0, v[150:151]
	s_mov_b32 m0, s91
	s_nop 0
	global_load_lds_dwordx4 v[214:215], off
	s_waitcnt vmcnt(8)
	s_waitcnt lgkmcnt(0)
	s_barrier
	s_setprio 1
	s_waitcnt lgkmcnt(0)
	v_mfma_f32_16x16x32_bf16 v[144:147], v[48:51], v[176:179], v[144:147]
	v_mfma_f32_16x16x32_bf16 v[140:143], v[64:67], v[176:179], v[140:143]
	v_mfma_f32_16x16x32_bf16 v[124:127], v[48:51], v[184:187], v[124:127]
	v_mfma_f32_16x16x32_bf16 v[120:123], v[64:67], v[184:187], v[120:123]
	v_mfma_f32_16x16x32_bf16 v[108:111], v[48:51], v[192:195], v[108:111]
	v_mfma_f32_16x16x32_bf16 v[104:107], v[64:67], v[192:195], v[104:107]
	v_mfma_f32_16x16x32_bf16 v[92:95], v[48:51], v[200:203], v[92:95]
	v_mfma_f32_16x16x32_bf16 v[88:91], v[64:67], v[200:203], v[88:91]
	v_mfma_f32_16x16x32_bf16 v[144:147], v[52:55], v[180:183], v[144:147]
	v_mfma_f32_16x16x32_bf16 v[140:143], v[68:71], v[180:183], v[140:143]
	v_mfma_f32_16x16x32_bf16 v[124:127], v[52:55], v[188:191], v[124:127]
	v_mfma_f32_16x16x32_bf16 v[120:123], v[68:71], v[188:191], v[120:123]
	v_mfma_f32_16x16x32_bf16 v[108:111], v[52:55], v[196:199], v[108:111]
	v_mfma_f32_16x16x32_bf16 v[104:107], v[68:71], v[196:199], v[104:107]
	v_mfma_f32_16x16x32_bf16 v[92:95], v[52:55], v[204:207], v[92:95]
	v_mfma_f32_16x16x32_bf16 v[88:91], v[68:71], v[204:207], v[88:91]
	v_mfma_f32_16x16x32_bf16 v[136:139], v[128:131], v[176:179], v[136:139]
	v_mfma_f32_16x16x32_bf16 v[132:135], v[168:171], v[176:179], v[132:135]
	v_mfma_f32_16x16x32_bf16 v[116:119], v[128:131], v[184:187], v[116:119]
	v_mfma_f32_16x16x32_bf16 v[112:115], v[168:171], v[184:187], v[112:115]
	v_mfma_f32_16x16x32_bf16 v[100:103], v[128:131], v[192:195], v[100:103]
	v_mfma_f32_16x16x32_bf16 v[96:99], v[168:171], v[192:195], v[96:99]
	v_mfma_f32_16x16x32_bf16 v[84:87], v[128:131], v[200:203], v[84:87]
	v_mfma_f32_16x16x32_bf16 v[80:83], v[168:171], v[200:203], v[80:83]
	v_mfma_f32_16x16x32_bf16 v[136:139], v[158:161], v[180:183], v[136:139]
	v_mfma_f32_16x16x32_bf16 v[132:135], v[172:175], v[180:183], v[132:135]
	v_mfma_f32_16x16x32_bf16 v[116:119], v[158:161], v[188:191], v[116:119]
	v_mfma_f32_16x16x32_bf16 v[112:115], v[172:175], v[188:191], v[112:115]
	v_mfma_f32_16x16x32_bf16 v[100:103], v[158:161], v[196:199], v[100:103]
	v_mfma_f32_16x16x32_bf16 v[96:99], v[172:175], v[196:199], v[96:99]
	v_mfma_f32_16x16x32_bf16 v[84:87], v[158:161], v[204:207], v[84:87]
	v_mfma_f32_16x16x32_bf16 v[80:83], v[172:175], v[204:207], v[80:83]
	s_setprio 0
	s_barrier
; #define PG8_STAGE(bufoff, gbase, voff) do { _Pragma("unroll") for (int _i = 0; _i < 2; ++_i) \
;         __builtin_amdgcn_global_load_lds((const unsigned*)((const char*)(gbase) + (voff)[_i]), (LAS unsigned*)(lds + (bufoff) + ldsw + _i * 8192), 16, 0, 0); } while (0)
; #define PG8_LDA(dst, b, h) do { _Pragma("unroll") for (int m = 0; m < 4; ++m) _Pragma("unroll") for (int k = 0; k < 2; ++k) dst[m][k] = *(const LAS bf16x8*)(lds + PG8_SA(b, h) + aoff + m * 2048 + k * 1024); } while (0)
; #define PG8_MMA(ai, bj, At, Bt) do { __builtin_amdgcn_s_setprio(1); _Pragma("unroll") for (int m = 0; m < 4; ++m) _Pragma("unroll") for (int n = 0; n < 2; ++n) _Pragma("unroll") for (int k = 0; k < 2; ++k) \
;         acc[ai][bj][m][n] = __builtin_amdgcn_mfma_f32_16x16x32_bf16(Bt[n][k], At[m][k], acc[ai][bj][m][n], 0, 0, 0); __builtin_amdgcn_s_setprio(0); } while (0)
; #define PG8_WAIT_V(n) asm volatile("s_waitcnt vmcnt(" #n ")" ::: "memory")
; #define PG8_WAIT_L(n) asm volatile("s_waitcnt lgkmcnt(" #n ")" ::: "memory")
; #define PG8_BAR __builtin_amdgcn_s_barrier()
; #define PG8_SCHED __builtin_amdgcn_sched_barrier(0)
; template <bool SP2 = true, class Epi, class Sched>
; __device__ __forceinline__ void gemm_phase(LAS unsigned char* lds, const int K, const int lda, const int ldb, const Sched& S, const Epi& E) {
;     ...
;         for (int t = 0; t < nt; t += 2) {
;     ...
;             PG8_LDA(At, 1, 1); PG8_STAGE(PG8_SB(1, 0), b3, voffB); PG8_STAGE(PG8_SB(1, 1), b3 + hstepB, voffB); PG8_STAGE(PG8_SA(1, 0), a3, voffA);
;             PG8_WAIT_V(8); PG8_WAIT_L(0); PG8_BAR; PG8_MMA(1, 0, At, B0); PG8_MMA(1, 1, At, B1); PG8_BAR; PG8_SCHED;
;     ...
;         if (wr == 0) PG8_BAR;
	s_add_i32 s49, s49, s87
	v_lshl_add_u64 v[162:163], v[162:163], 0, s[72:73]
	s_mov_b32 m0, s49
	ds_read_b128 v[176:179], v167 offset:49152
	ds_read_b128 v[180:183], v167 offset:50176
	ds_read_b128 v[184:187], v167 offset:51200
	ds_read_b128 v[188:191], v167 offset:52224
	ds_read_b128 v[192:195], v167 offset:53248
	ds_read_b128 v[196:199], v167 offset:54272
	ds_read_b128 v[200:203], v167 offset:55296
	ds_read_b128 v[204:207], v167 offset:56320
	global_load_lds_dwordx4 v[162:163], off
	s_add_i32 m0, s49, 0x2000
	s_add_u32 s82, s82, 0x40080
	v_lshl_add_u64 v[162:163], v[208:209], 0, s[72:73]
	s_addc_u32 s83, s83, 0
	s_add_i32 s49, s94, s87
	global_load_lds_dwordx4 v[162:163], off
	v_lshl_add_u64 v[162:163], s[82:83], 0, v[224:225]
	s_mov_b32 m0, s49
	s_nop 0
	global_load_lds_dwordx4 v[162:163], off
	v_lshl_add_u64 v[162:163], s[82:83], 0, v[148:149]
	s_add_i32 m0, s49, 0x2000
	s_nop 0
	global_load_lds_dwordx4 v[162:163], off
	v_lshl_add_u64 v[162:163], v[210:211], 0, s[72:73]
	s_mov_b32 m0, s70
	s_nop 0
	global_load_lds_dwordx4 v[162:163], off
	v_lshl_add_u64 v[162:163], v[212:213], 0, s[72:73]
	s_mov_b32 m0, s92
	s_nop 0
	global_load_lds_dwordx4 v[162:163], off
	s_waitcnt vmcnt(8)
	s_waitcnt lgkmcnt(0)
	s_barrier
	s_setprio 1
	s_waitcnt lgkmcnt(0)
	v_mfma_f32_16x16x32_bf16 v[76:79], v[48:51], v[176:179], v[76:79]
	v_mfma_f32_16x16x32_bf16 v[72:75], v[64:67], v[176:179], v[72:75]
	v_mfma_f32_16x16x32_bf16 v[60:63], v[48:51], v[184:187], v[60:63]
	v_mfma_f32_16x16x32_bf16 v[56:59], v[64:67], v[184:187], v[56:59]
	v_mfma_f32_16x16x32_bf16 v[44:47], v[48:51], v[192:195], v[44:47]
	v_mfma_f32_16x16x32_bf16 v[40:43], v[64:67], v[192:195], v[40:43]
	v_mfma_f32_16x16x32_bf16 v[12:15], v[48:51], v[200:203], v[12:15]
	v_mfma_f32_16x16x32_bf16 v[8:11], v[64:67], v[200:203], v[8:11]
	v_mfma_f32_16x16x32_bf16 v[76:79], v[52:55], v[180:183], v[76:79]
	v_mfma_f32_16x16x32_bf16 v[72:75], v[68:71], v[180:183], v[72:75]
	v_mfma_f32_16x16x32_bf16 v[60:63], v[52:55], v[188:191], v[60:63]
	v_mfma_f32_16x16x32_bf16 v[56:59], v[68:71], v[188:191], v[56:59]
	v_mfma_f32_16x16x32_bf16 v[44:47], v[52:55], v[196:199], v[44:47]
	v_mfma_f32_16x16x32_bf16 v[40:43], v[68:71], v[196:199], v[40:43]
	v_mfma_f32_16x16x32_bf16 v[12:15], v[52:55], v[204:207], v[12:15]
	v_mfma_f32_16x16x32_bf16 v[8:11], v[68:71], v[204:207], v[8:11]
	v_mfma_f32_16x16x32_bf16 v[16:19], v[128:131], v[176:179], v[16:19]
	v_mfma_f32_16x16x32_bf16 v[68:71], v[158:161], v[180:183], v[16:19]
	v_mfma_f32_16x16x32_bf16 v[16:19], v[168:171], v[176:179], v[20:23]
	v_mfma_f32_16x16x32_bf16 v[64:67], v[172:175], v[180:183], v[16:19]
	v_mfma_f32_16x16x32_bf16 v[16:19], v[128:131], v[184:187], v[24:27]
	v_mfma_f32_16x16x32_bf16 v[52:55], v[158:161], v[188:191], v[16:19]
	v_mfma_f32_16x16x32_bf16 v[16:19], v[168:171], v[184:187], v[28:31]
	v_mfma_f32_16x16x32_bf16 v[48:51], v[172:175], v[188:191], v[16:19]
	v_mfma_f32_16x16x32_bf16 v[16:19], v[128:131], v[192:195], v[36:39]
	v_mfma_f32_16x16x32_bf16 v[36:39], v[158:161], v[196:199], v[16:19]
	v_mfma_f32_16x16x32_bf16 v[16:19], v[168:171], v[192:195], v[32:35]
	v_mfma_f32_16x16x32_bf16 v[4:7], v[128:131], v[200:203], v[4:7]
	v_mfma_f32_16x16x32_bf16 v[0:3], v[168:171], v[200:203], v[0:3]
	v_mfma_f32_16x16x32_bf16 v[32:35], v[172:175], v[196:199], v[16:19]
	v_mfma_f32_16x16x32_bf16 v[4:7], v[158:161], v[204:207], v[4:7]
	v_mfma_f32_16x16x32_bf16 v[0:3], v[172:175], v[204:207], v[0:3]
	s_setprio 0
	s_barrier
	s_add_i32 s48, s48, 2
	s_add_u32 s30, s30, 0x100
	s_addc_u32 s31, s31, 0
	s_add_u32 s23, s23, 0x100
	s_addc_u32 s25, s25, 0
	s_cmp_gt_u32 s48, 13
	s_cbranch_scc0 .LBB0_606
	s_and_b64 vcc, exec, s[20:21]
	s_cbranch_vccz .LBB0_609
	s_barrier

; #define PG8_STAGE(bufoff, gbase, voff) do { _Pragma("unroll") for (int _i = 0; _i < 2; ++_i) \
;         __builtin_amdgcn_global_load_lds((const unsigned*)((const char*)(gbase) + (voff)[_i]), (LAS unsigned*)(lds + (bufoff) + ldsw + _i * 8192), 16, 0, 0); } while (0)
; #define PG8_LDA(dst, b, h) do { _Pragma("unroll") for (int m = 0; m < 4; ++m) _Pragma("unroll") for (int k = 0; k < 2; ++k) dst[m][k] = *(const LAS bf16x8*)(lds + PG8_SA(b, h) + aoff + m * 2048 + k * 1024); } while (0)
; #define PG8_LDB(dst, b, h) do { _Pragma("unroll") for (int n = 0; n < 2; ++n) _Pragma("unroll") for (int k = 0; k < 2; ++k) dst[n][k] = *(const LAS bf16x8*)(lds + PG8_SB(b, h) + boff + n * 2048 + k * 1024); } while (0)
; #define PG8_MMA(ai, bj, At, Bt) do { __builtin_amdgcn_s_setprio(1); _Pragma("unroll") for (int m = 0; m < 4; ++m) _Pragma("unroll") for (int n = 0; n < 2; ++n) _Pragma("unroll") for (int k = 0; k < 2; ++k) \
;         acc[ai][bj][m][n] = __builtin_amdgcn_mfma_f32_16x16x32_bf16(Bt[n][k], At[m][k], acc[ai][bj][m][n], 0, 0, 0); __builtin_amdgcn_s_setprio(0); } while (0)
; #define PG8_WAIT_V(n) asm volatile("s_waitcnt vmcnt(" #n ")" ::: "memory")
; #define PG8_WAIT_L(n) asm volatile("s_waitcnt lgkmcnt(" #n ")" ::: "memory")
; #define PG8_BAR __builtin_amdgcn_s_barrier()
; #define PG8_SCHED __builtin_amdgcn_sched_barrier(0)
; template <bool SP2 = true, class Epi, class Sched>
; __device__ __forceinline__ void gemm_phase(LAS unsigned char* lds, const int K, const int lda, const int ldb, const Sched& S, const Epi& E) {
;     ...
;         for (int t = 0; t < nt; t += 2) {
;             const bool last = (t == nt - 2);
;             const char* a1 = cA + (unsigned)(t + 1) * kstep;
;             const char* a2 = last ? nA : cA + (unsigned)(t + 2) * kstep; const char* b2 = last ? nB : cB + (unsigned)(t + 2) * kstep;
;             const char* a3 = a2 + kstep; const char* b3 = b2 + kstep;
;             if constexpr (SP2) {
;             PG8_LDB(B0, 0, 0); PG8_LDB(B1, 0, 1); PG8_SCHED; PG8_LDA(At, 0, 0); PG8_STAGE(PG8_SA(1, 1), a1 + hstepA, voffA);
;             PG8_WAIT_V(8); PG8_WAIT_L(0); PG8_BAR; PG8_MMA(0, 0, At, B0); PG8_MMA(0, 1, At, B1); PG8_BAR; PG8_SCHED;
;             PG8_LDA(At, 0, 1); PG8_STAGE(PG8_SB(0, 0), b2, voffB); PG8_STAGE(PG8_SB(0, 1), b2 + hstepB, voffB); PG8_STAGE(PG8_SA(0, 0), a2, voffA);
.LBB0_676:
	s_add_u32 s65, s6, 0xfff80080
	s_addc_u32 s82, s7, -1
	s_add_i32 s86, 0, 0x10000
	s_cmp_eq_u32 s64, 28
	s_cselect_b32 s85, s38, s82
	s_cselect_b32 s84, s49, s65
	s_cselect_b32 s83, s23, s9
	s_cselect_b32 s82, s22, s8
	s_add_i32 s65, 0, 0x14000
	v_add_u32_e32 v140, s86, v237
	v_add_u32_e32 v156, s65, v237
	ds_read_b128 v[112:115], v140
	ds_read_b128 v[116:119], v140 offset:1024
	ds_read_b128 v[128:131], v140 offset:2048
	ds_read_b128 v[140:143], v140 offset:3072
	ds_read_b128 v[144:147], v156
	ds_read_b128 v[148:151], v156 offset:1024
	ds_read_b128 v[152:155], v156 offset:2048
	ds_read_b128 v[156:159], v156 offset:3072
	v_lshl_add_u64 v[212:213], s[6:7], 0, v[200:201]
	s_add_i32 m0, s88, 0xc000
	ds_read_b128 v[160:163], v253
	ds_read_b128 v[164:167], v253 offset:1024
	ds_read_b128 v[168:171], v253 offset:2048
	ds_read_b128 v[172:175], v253 offset:3072
	ds_read_b128 v[176:179], v253 offset:4096
	ds_read_b128 v[180:183], v253 offset:5120
	ds_read_b128 v[204:207], v253 offset:6144
	ds_read_b128 v[208:211], v253 offset:7168
	global_load_lds_dwordx4 v[212:213], off
	v_lshl_add_u64 v[212:213], s[6:7], 0, v[202:203]
	s_add_i32 m0, s88, 0xe000
	s_nop 0
	global_load_lds_dwordx4 v[212:213], off
	s_waitcnt vmcnt(8)
	s_waitcnt lgkmcnt(0)
	s_barrier
	s_setprio 1
	s_waitcnt lgkmcnt(0)
	v_mfma_f32_16x16x32_bf16 v[124:127], v[112:115], v[160:163], v[124:127]
	v_mfma_f32_16x16x32_bf16 v[120:123], v[128:131], v[160:163], v[120:123]
	v_mfma_f32_16x16x32_bf16 v[108:111], v[112:115], v[168:171], v[108:111]
	v_mfma_f32_16x16x32_bf16 v[104:107], v[128:131], v[168:171], v[104:107]
	v_mfma_f32_16x16x32_bf16 v[92:95], v[112:115], v[176:179], v[92:95]
	v_mfma_f32_16x16x32_bf16 v[88:91], v[128:131], v[176:179], v[88:91]
	v_mfma_f32_16x16x32_bf16 v[76:79], v[112:115], v[204:207], v[76:79]
	v_mfma_f32_16x16x32_bf16 v[72:75], v[128:131], v[204:207], v[72:75]
	v_mfma_f32_16x16x32_bf16 v[124:127], v[116:119], v[164:167], v[124:127]
	v_mfma_f32_16x16x32_bf16 v[120:123], v[140:143], v[164:167], v[120:123]
	v_mfma_f32_16x16x32_bf16 v[108:111], v[116:119], v[172:175], v[108:111]
	v_mfma_f32_16x16x32_bf16 v[104:107], v[140:143], v[172:175], v[104:107]
	v_mfma_f32_16x16x32_bf16 v[92:95], v[116:119], v[180:183], v[92:95]
	v_mfma_f32_16x16x32_bf16 v[88:91], v[140:143], v[180:183], v[88:91]
	v_mfma_f32_16x16x32_bf16 v[76:79], v[116:119], v[208:211], v[76:79]
	v_mfma_f32_16x16x32_bf16 v[72:75], v[140:143], v[208:211], v[72:75]
	v_mfma_f32_16x16x32_bf16 v[136:139], v[144:147], v[160:163], v[136:139]
	v_mfma_f32_16x16x32_bf16 v[132:135], v[152:155], v[160:163], v[132:135]
	v_mfma_f32_16x16x32_bf16 v[100:103], v[144:147], v[168:171], v[100:103]
	v_mfma_f32_16x16x32_bf16 v[96:99], v[152:155], v[168:171], v[96:99]
	v_mfma_f32_16x16x32_bf16 v[84:87], v[144:147], v[176:179], v[84:87]
	v_mfma_f32_16x16x32_bf16 v[80:83], v[152:155], v[176:179], v[80:83]
	v_mfma_f32_16x16x32_bf16 v[68:71], v[144:147], v[204:207], v[68:71]
	v_mfma_f32_16x16x32_bf16 v[64:67], v[152:155], v[204:207], v[64:67]
	v_mfma_f32_16x16x32_bf16 v[136:139], v[148:151], v[164:167], v[136:139]
	v_mfma_f32_16x16x32_bf16 v[132:135], v[156:159], v[164:167], v[132:135]
	v_mfma_f32_16x16x32_bf16 v[100:103], v[148:151], v[172:175], v[100:103]
	v_mfma_f32_16x16x32_bf16 v[96:99], v[156:159], v[172:175], v[96:99]
	v_mfma_f32_16x16x32_bf16 v[84:87], v[148:151], v[180:183], v[84:87]
	v_mfma_f32_16x16x32_bf16 v[80:83], v[156:159], v[180:183], v[80:83]
	v_mfma_f32_16x16x32_bf16 v[68:71], v[148:151], v[208:211], v[68:71]
	v_mfma_f32_16x16x32_bf16 v[64:67], v[156:159], v[208:211], v[64:67]
	s_setprio 0
	s_barrier
	s_add_i32 s86, s86, s69
	v_lshl_add_u64 v[212:213], s[82:83], 0, v[186:187]
	s_mov_b32 m0, s86
	ds_read_b128 v[160:163], v253 offset:16384
	ds_read_b128 v[164:167], v253 offset:17408
	ds_read_b128 v[168:171], v253 offset:18432
	ds_read_b128 v[172:175], v253 offset:19456
	ds_read_b128 v[176:179], v253 offset:20480
	ds_read_b128 v[180:183], v253 offset:21504
	ds_read_b128 v[204:207], v253 offset:22528
	ds_read_b128 v[208:211], v253 offset:23552
	global_load_lds_dwordx4 v[212:213], off
	s_add_i32 m0, s86, 0x2000
	s_add_u32 s86, s82, 0x80000
	v_lshl_add_u64 v[214:215], s[82:83], 0, v[190:191]
	s_addc_u32 s87, s83, 0
	s_add_i32 s65, s65, s69
	global_load_lds_dwordx4 v[214:215], off
	v_lshl_add_u64 v[216:217], s[86:87], 0, v[186:187]
	s_mov_b32 m0, s65
	v_lshl_add_u64 v[218:219], s[84:85], 0, v[188:189]
	global_load_lds_dwordx4 v[216:217], off
	v_lshl_add_u64 v[216:217], s[86:87], 0, v[190:191]
	s_add_i32 m0, s65, 0x2000
	s_nop 0
	global_load_lds_dwordx4 v[216:217], off
	v_lshl_add_u64 v[216:217], s[84:85], 0, v[184:185]
	s_mov_b32 m0, s88
	s_nop 0
	global_load_lds_dwordx4 v[216:217], off
	s_mov_b32 m0, s89
	s_nop 0
	global_load_lds_dwordx4 v[218:219], off
	s_waitcnt vmcnt(8)
	s_waitcnt lgkmcnt(0)
	s_barrier
; #define PG8_STAGE(bufoff, gbase, voff) do { _Pragma("unroll") for (int _i = 0; _i < 2; ++_i) \
;         __builtin_amdgcn_global_load_lds((const unsigned*)((const char*)(gbase) + (voff)[_i]), (LAS unsigned*)(lds + (bufoff) + ldsw + _i * 8192), 16, 0, 0); } while (0)
; #define PG8_LDA(dst, b, h) do { _Pragma("unroll") for (int m = 0; m < 4; ++m) _Pragma("unroll") for (int k = 0; k < 2; ++k) dst[m][k] = *(const LAS bf16x8*)(lds + PG8_SA(b, h) + aoff + m * 2048 + k * 1024); } while (0)
; #define PG8_LDB(dst, b, h) do { _Pragma("unroll") for (int n = 0; n < 2; ++n) _Pragma("unroll") for (int k = 0; k < 2; ++k) dst[n][k] = *(const LAS bf16x8*)(lds + PG8_SB(b, h) + boff + n * 2048 + k * 1024); } while (0)
; #define PG8_MMA(ai, bj, At, Bt) do { __builtin_amdgcn_s_setprio(1); _Pragma("unroll") for (int m = 0; m < 4; ++m) _Pragma("unroll") for (int n = 0; n < 2; ++n) _Pragma("unroll") for (int k = 0; k < 2; ++k) \
;         acc[ai][bj][m][n] = __builtin_amdgcn_mfma_f32_16x16x32_bf16(Bt[n][k], At[m][k], acc[ai][bj][m][n], 0, 0, 0); __builtin_amdgcn_s_setprio(0); } while (0)
; #define PG8_WAIT_V(n) asm volatile("s_waitcnt vmcnt(" #n ")" ::: "memory")
; #define PG8_WAIT_L(n) asm volatile("s_waitcnt lgkmcnt(" #n ")" ::: "memory")
; #define PG8_BAR __builtin_amdgcn_s_barrier()
; #define PG8_SCHED __builtin_amdgcn_sched_barrier(0)
; template <bool SP2 = true, class Epi, class Sched>
; __device__ __forceinline__ void gemm_phase(LAS unsigned char* lds, const int K, const int lda, const int ldb, const Sched& S, const Epi& E) {
;     ...
;             PG8_WAIT_V(8); PG8_WAIT_L(0); PG8_BAR; PG8_MMA(0, 0, At, B0); PG8_MMA(0, 1, At, B1); PG8_BAR; PG8_SCHED;
;             PG8_LDA(At, 0, 1); PG8_STAGE(PG8_SB(0, 0), b2, voffB); PG8_STAGE(PG8_SB(0, 1), b2 + hstepB, voffB); PG8_STAGE(PG8_SA(0, 0), a2, voffA);
;             PG8_WAIT_V(8); PG8_WAIT_L(0); PG8_BAR; PG8_MMA(1, 0, At, B0); PG8_MMA(1, 1, At, B1); PG8_BAR; PG8_SCHED;
;             PG8_LDB(B0, 1, 0); PG8_LDB(B1, 1, 1); PG8_SCHED; PG8_LDA(At, 1, 0); PG8_STAGE(PG8_SA(0, 1), a2 + hstepA, voffA);
;             PG8_WAIT_V(8); PG8_WAIT_L(0); PG8_BAR; PG8_MMA(0, 0, At, B0); PG8_MMA(0, 1, At, B1); PG8_BAR; PG8_SCHED;
	s_setprio 1
	s_waitcnt lgkmcnt(0)
	v_mfma_f32_16x16x32_bf16 v[60:63], v[112:115], v[160:163], v[60:63]
	v_mfma_f32_16x16x32_bf16 v[56:59], v[128:131], v[160:163], v[56:59]
	v_mfma_f32_16x16x32_bf16 v[44:47], v[112:115], v[168:171], v[44:47]
	v_mfma_f32_16x16x32_bf16 v[40:43], v[128:131], v[168:171], v[40:43]
	v_mfma_f32_16x16x32_bf16 v[28:31], v[112:115], v[176:179], v[28:31]
	v_mfma_f32_16x16x32_bf16 v[24:27], v[128:131], v[176:179], v[24:27]
	v_mfma_f32_16x16x32_bf16 v[12:15], v[112:115], v[204:207], v[12:15]
	v_mfma_f32_16x16x32_bf16 v[8:11], v[128:131], v[204:207], v[8:11]
	v_mfma_f32_16x16x32_bf16 v[60:63], v[116:119], v[164:167], v[60:63]
	v_mfma_f32_16x16x32_bf16 v[56:59], v[140:143], v[164:167], v[56:59]
	v_mfma_f32_16x16x32_bf16 v[44:47], v[116:119], v[172:175], v[44:47]
	v_mfma_f32_16x16x32_bf16 v[40:43], v[140:143], v[172:175], v[40:43]
	v_mfma_f32_16x16x32_bf16 v[28:31], v[116:119], v[180:183], v[28:31]
	v_mfma_f32_16x16x32_bf16 v[24:27], v[140:143], v[180:183], v[24:27]
	v_mfma_f32_16x16x32_bf16 v[12:15], v[116:119], v[208:211], v[12:15]
	v_mfma_f32_16x16x32_bf16 v[8:11], v[140:143], v[208:211], v[8:11]
	v_mfma_f32_16x16x32_bf16 v[52:55], v[144:147], v[160:163], v[52:55]
	v_mfma_f32_16x16x32_bf16 v[48:51], v[152:155], v[160:163], v[48:51]
	v_mfma_f32_16x16x32_bf16 v[36:39], v[144:147], v[168:171], v[36:39]
	v_mfma_f32_16x16x32_bf16 v[32:35], v[152:155], v[168:171], v[32:35]
	v_mfma_f32_16x16x32_bf16 v[20:23], v[144:147], v[176:179], v[20:23]
	v_mfma_f32_16x16x32_bf16 v[16:19], v[152:155], v[176:179], v[16:19]
	v_mfma_f32_16x16x32_bf16 v[4:7], v[144:147], v[204:207], v[4:7]
	v_mfma_f32_16x16x32_bf16 v[0:3], v[152:155], v[204:207], v[0:3]
	v_mfma_f32_16x16x32_bf16 v[52:55], v[148:151], v[164:167], v[52:55]
	v_mfma_f32_16x16x32_bf16 v[48:51], v[156:159], v[164:167], v[48:51]
	v_mfma_f32_16x16x32_bf16 v[36:39], v[148:151], v[172:175], v[36:39]
	v_mfma_f32_16x16x32_bf16 v[32:35], v[156:159], v[172:175], v[32:35]
	v_mfma_f32_16x16x32_bf16 v[20:23], v[148:151], v[180:183], v[20:23]
	v_mfma_f32_16x16x32_bf16 v[16:19], v[156:159], v[180:183], v[16:19]
	v_mfma_f32_16x16x32_bf16 v[4:7], v[148:151], v[208:211], v[4:7]
	v_mfma_f32_16x16x32_bf16 v[0:3], v[156:159], v[208:211], v[0:3]
	s_setprio 0
	s_barrier
	s_add_i32 s65, 0, 0x18000
	s_add_i32 s86, 0, 0x1c000
	v_add_u32_e32 v140, s65, v237
	v_add_u32_e32 v156, s86, v237
	ds_read_b128 v[112:115], v140
	ds_read_b128 v[116:119], v140 offset:1024
	ds_read_b128 v[128:131], v140 offset:2048
	ds_read_b128 v[140:143], v140 offset:3072
	ds_read_b128 v[144:147], v156
	ds_read_b128 v[148:151], v156 offset:1024
	ds_read_b128 v[152:155], v156 offset:2048
	ds_read_b128 v[156:159], v156 offset:3072
	s_add_u32 s84, s84, 0x80000
	s_addc_u32 s85, s85, 0
	s_mov_b32 m0, s90
	v_lshl_add_u64 v[220:221], s[84:85], 0, v[184:185]
	ds_read_b128 v[160:163], v253 offset:32768
	ds_read_b128 v[164:167], v253 offset:33792
	ds_read_b128 v[168:171], v253 offset:34816
	ds_read_b128 v[172:175], v253 offset:35840
	ds_read_b128 v[176:179], v253 offset:36864
	ds_read_b128 v[180:183], v253 offset:37888
	ds_read_b128 v[204:207], v253 offset:38912
	ds_read_b128 v[208:211], v253 offset:39936
	global_load_lds_dwordx4 v[220:221], off
	v_lshl_add_u64 v[220:221], s[84:85], 0, v[188:189]
	s_mov_b32 m0, s91
	s_nop 0
	global_load_lds_dwordx4 v[220:221], off
	s_waitcnt vmcnt(8)
	s_waitcnt lgkmcnt(0)
	s_barrier
	s_setprio 1
	s_waitcnt lgkmcnt(0)
	v_mfma_f32_16x16x32_bf16 v[124:127], v[112:115], v[160:163], v[124:127]
	v_mfma_f32_16x16x32_bf16 v[120:123], v[128:131], v[160:163], v[120:123]
	v_mfma_f32_16x16x32_bf16 v[108:111], v[112:115], v[168:171], v[108:111]
	v_mfma_f32_16x16x32_bf16 v[104:107], v[128:131], v[168:171], v[104:107]
	v_mfma_f32_16x16x32_bf16 v[92:95], v[112:115], v[176:179], v[92:95]
	v_mfma_f32_16x16x32_bf16 v[88:91], v[128:131], v[176:179], v[88:91]
	v_mfma_f32_16x16x32_bf16 v[76:79], v[112:115], v[204:207], v[76:79]
	v_mfma_f32_16x16x32_bf16 v[72:75], v[128:131], v[204:207], v[72:75]
	v_mfma_f32_16x16x32_bf16 v[124:127], v[116:119], v[164:167], v[124:127]
	v_mfma_f32_16x16x32_bf16 v[120:123], v[140:143], v[164:167], v[120:123]
	v_mfma_f32_16x16x32_bf16 v[108:111], v[116:119], v[172:175], v[108:111]
	v_mfma_f32_16x16x32_bf16 v[104:107], v[140:143], v[172:175], v[104:107]
	v_mfma_f32_16x16x32_bf16 v[92:95], v[116:119], v[180:183], v[92:95]
	v_mfma_f32_16x16x32_bf16 v[88:91], v[140:143], v[180:183], v[88:91]
	v_mfma_f32_16x16x32_bf16 v[76:79], v[116:119], v[208:211], v[76:79]
	v_mfma_f32_16x16x32_bf16 v[72:75], v[140:143], v[208:211], v[72:75]
	v_mfma_f32_16x16x32_bf16 v[136:139], v[144:147], v[160:163], v[136:139]
	v_mfma_f32_16x16x32_bf16 v[132:135], v[152:155], v[160:163], v[132:135]
	v_mfma_f32_16x16x32_bf16 v[100:103], v[144:147], v[168:171], v[100:103]
	v_mfma_f32_16x16x32_bf16 v[96:99], v[152:155], v[168:171], v[96:99]
	v_mfma_f32_16x16x32_bf16 v[84:87], v[144:147], v[176:179], v[84:87]
	v_mfma_f32_16x16x32_bf16 v[80:83], v[152:155], v[176:179], v[80:83]
	v_mfma_f32_16x16x32_bf16 v[68:71], v[144:147], v[204:207], v[68:71]
	v_mfma_f32_16x16x32_bf16 v[64:67], v[152:155], v[204:207], v[64:67]
	v_mfma_f32_16x16x32_bf16 v[136:139], v[148:151], v[164:167], v[136:139]
	v_mfma_f32_16x16x32_bf16 v[132:135], v[156:159], v[164:167], v[132:135]
	v_mfma_f32_16x16x32_bf16 v[100:103], v[148:151], v[172:175], v[100:103]
	v_mfma_f32_16x16x32_bf16 v[96:99], v[156:159], v[172:175], v[96:99]
	v_mfma_f32_16x16x32_bf16 v[84:87], v[148:151], v[180:183], v[84:87]
	v_mfma_f32_16x16x32_bf16 v[80:83], v[156:159], v[180:183], v[80:83]
	v_mfma_f32_16x16x32_bf16 v[68:71], v[148:151], v[208:211], v[68:71]
	v_mfma_f32_16x16x32_bf16 v[64:67], v[156:159], v[208:211], v[64:67]
	s_setprio 0
	s_barrier
; #define PG8_STAGE(bufoff, gbase, voff) do { _Pragma("unroll") for (int _i = 0; _i < 2; ++_i) \
;         __builtin_amdgcn_global_load_lds((const unsigned*)((const char*)(gbase) + (voff)[_i]), (LAS unsigned*)(lds + (bufoff) + ldsw + _i * 8192), 16, 0, 0); } while (0)
; #define PG8_LDA(dst, b, h) do { _Pragma("unroll") for (int m = 0; m < 4; ++m) _Pragma("unroll") for (int k = 0; k < 2; ++k) dst[m][k] = *(const LAS bf16x8*)(lds + PG8_SA(b, h) + aoff + m * 2048 + k * 1024); } while (0)
; #define PG8_MMA(ai, bj, At, Bt) do { __builtin_amdgcn_s_setprio(1); _Pragma("unroll") for (int m = 0; m < 4; ++m) _Pragma("unroll") for (int n = 0; n < 2; ++n) _Pragma("unroll") for (int k = 0; k < 2; ++k) \
;         acc[ai][bj][m][n] = __builtin_amdgcn_mfma_f32_16x16x32_bf16(Bt[n][k], At[m][k], acc[ai][bj][m][n], 0, 0, 0); __builtin_amdgcn_s_setprio(0); } while (0)
; #define PG8_WAIT_V(n) asm volatile("s_waitcnt vmcnt(" #n ")" ::: "memory")
; #define PG8_WAIT_L(n) asm volatile("s_waitcnt lgkmcnt(" #n ")" ::: "memory")
; #define PG8_BAR __builtin_amdgcn_s_barrier()
; #define PG8_SCHED __builtin_amdgcn_sched_barrier(0)
; template <bool SP2 = true, class Epi, class Sched>
; __device__ __forceinline__ void gemm_phase(LAS unsigned char* lds, const int K, const int lda, const int ldb, const Sched& S, const Epi& E) {
;     ...
;         for (int t = 0; t < nt; t += 2) {
;     ...
;             PG8_LDA(At, 1, 1); PG8_STAGE(PG8_SB(1, 0), b3, voffB); PG8_STAGE(PG8_SB(1, 1), b3 + hstepB, voffB); PG8_STAGE(PG8_SA(1, 0), a3, voffA);
;             PG8_WAIT_V(8); PG8_WAIT_L(0); PG8_BAR; PG8_MMA(1, 0, At, B0); PG8_MMA(1, 1, At, B1); PG8_BAR; PG8_SCHED;
;     ...
;         if (wr == 0) PG8_BAR;
	s_add_i32 s65, s65, s69
	v_lshl_add_u64 v[212:213], v[212:213], 0, s[72:73]
	s_mov_b32 m0, s65
	ds_read_b128 v[160:163], v253 offset:49152
	ds_read_b128 v[164:167], v253 offset:50176
	ds_read_b128 v[168:171], v253 offset:51200
	ds_read_b128 v[172:175], v253 offset:52224
	ds_read_b128 v[176:179], v253 offset:53248
	ds_read_b128 v[180:183], v253 offset:54272
	ds_read_b128 v[204:207], v253 offset:55296
	ds_read_b128 v[208:211], v253 offset:56320
	global_load_lds_dwordx4 v[212:213], off
	s_add_i32 m0, s65, 0x2000
	s_add_u32 s82, s82, 0x80080
	v_lshl_add_u64 v[212:213], v[214:215], 0, s[72:73]
	s_addc_u32 s83, s83, 0
	s_add_i32 s65, s86, s69
	global_load_lds_dwordx4 v[212:213], off
	v_lshl_add_u64 v[212:213], s[82:83], 0, v[186:187]
	s_mov_b32 m0, s65
	s_nop 0
	global_load_lds_dwordx4 v[212:213], off
	v_lshl_add_u64 v[212:213], s[82:83], 0, v[190:191]
	s_add_i32 m0, s65, 0x2000
	s_nop 0
	global_load_lds_dwordx4 v[212:213], off
	v_lshl_add_u64 v[212:213], v[216:217], 0, s[72:73]
	s_mov_b32 m0, s97
	s_nop 0
	global_load_lds_dwordx4 v[212:213], off
	v_lshl_add_u64 v[212:213], v[218:219], 0, s[72:73]
	s_mov_b32 m0, s37
	s_nop 0
	global_load_lds_dwordx4 v[212:213], off
	s_waitcnt vmcnt(8)
	s_waitcnt lgkmcnt(0)
	s_barrier
	s_setprio 1
	s_waitcnt lgkmcnt(0)
	v_mfma_f32_16x16x32_bf16 v[60:63], v[112:115], v[160:163], v[60:63]
	v_mfma_f32_16x16x32_bf16 v[56:59], v[128:131], v[160:163], v[56:59]
	v_mfma_f32_16x16x32_bf16 v[44:47], v[112:115], v[168:171], v[44:47]
	v_mfma_f32_16x16x32_bf16 v[40:43], v[128:131], v[168:171], v[40:43]
	v_mfma_f32_16x16x32_bf16 v[28:31], v[112:115], v[176:179], v[28:31]
	v_mfma_f32_16x16x32_bf16 v[24:27], v[128:131], v[176:179], v[24:27]
	v_mfma_f32_16x16x32_bf16 v[12:15], v[112:115], v[204:207], v[12:15]
	v_mfma_f32_16x16x32_bf16 v[8:11], v[128:131], v[204:207], v[8:11]
	v_mfma_f32_16x16x32_bf16 v[60:63], v[116:119], v[164:167], v[60:63]
	v_mfma_f32_16x16x32_bf16 v[56:59], v[140:143], v[164:167], v[56:59]
	v_mfma_f32_16x16x32_bf16 v[44:47], v[116:119], v[172:175], v[44:47]
	v_mfma_f32_16x16x32_bf16 v[40:43], v[140:143], v[172:175], v[40:43]
	v_mfma_f32_16x16x32_bf16 v[28:31], v[116:119], v[180:183], v[28:31]
	v_mfma_f32_16x16x32_bf16 v[24:27], v[140:143], v[180:183], v[24:27]
	v_mfma_f32_16x16x32_bf16 v[12:15], v[116:119], v[208:211], v[12:15]
	v_mfma_f32_16x16x32_bf16 v[8:11], v[140:143], v[208:211], v[8:11]
	v_mfma_f32_16x16x32_bf16 v[52:55], v[144:147], v[160:163], v[52:55]
	v_mfma_f32_16x16x32_bf16 v[48:51], v[152:155], v[160:163], v[48:51]
	v_mfma_f32_16x16x32_bf16 v[36:39], v[144:147], v[168:171], v[36:39]
	v_mfma_f32_16x16x32_bf16 v[32:35], v[152:155], v[168:171], v[32:35]
	v_mfma_f32_16x16x32_bf16 v[20:23], v[144:147], v[176:179], v[20:23]
	v_mfma_f32_16x16x32_bf16 v[16:19], v[152:155], v[176:179], v[16:19]
	v_mfma_f32_16x16x32_bf16 v[4:7], v[144:147], v[204:207], v[4:7]
	v_mfma_f32_16x16x32_bf16 v[0:3], v[152:155], v[204:207], v[0:3]
	v_mfma_f32_16x16x32_bf16 v[52:55], v[148:151], v[164:167], v[52:55]
	v_mfma_f32_16x16x32_bf16 v[48:51], v[156:159], v[164:167], v[48:51]
	v_mfma_f32_16x16x32_bf16 v[36:39], v[148:151], v[172:175], v[36:39]
	v_mfma_f32_16x16x32_bf16 v[32:35], v[156:159], v[172:175], v[32:35]
	v_mfma_f32_16x16x32_bf16 v[20:23], v[148:151], v[180:183], v[20:23]
	v_mfma_f32_16x16x32_bf16 v[16:19], v[156:159], v[180:183], v[16:19]
	v_mfma_f32_16x16x32_bf16 v[4:7], v[148:151], v[208:211], v[4:7]
	v_mfma_f32_16x16x32_bf16 v[0:3], v[156:159], v[208:211], v[0:3]
	s_setprio 0
	s_barrier
	s_add_i32 s64, s64, 2
	s_add_u32 s6, s6, 0x100
	s_addc_u32 s7, s7, 0
	s_add_u32 s8, s8, 0x100
	s_addc_u32 s9, s9, 0
	s_cmp_gt_u32 s64, 29
	s_cbranch_scc0 .LBB0_676
	s_and_b64 vcc, exec, s[26:27]
	s_cbranch_vccz .LBB0_679
	s_barrier
